# attention tile loop: exact vmcnt waits for K/V staging instead of full drain each iteration
# baseline (speedup 1.0000x reference)
; __device__ __forceinline__ void qk_fin(f32x16& n0, f32x16& n1, const char* Ks, const bf16x8* qr, int r32, int hi, int cbase,
;                                        const f32x16& q0, const f32x16& q1, float& l_reg, bf16x8& pa0, bf16x8& pa1, bf16x8& pa2, bf16x8& pa3) {
;   float ps = 0.f;
;   { const bf16x8 k0 = KFRAG(0, 0), k1 = KFRAG(0, 1); n0 = __builtin_amdgcn_mfma_f32_32x32x16_bf16(k0, qr[0], n0, 0, 0, 0); n1 = __builtin_amdgcn_mfma_f32_32x32x16_bf16(k1, qr[0], n1, 0, 0, 0); }
; #pragma unroll
;   for (int r = 0; r < 8; ++r) ps += q0[r];
;   PK4(q0, 0, pa0); asm volatile("" : "+v"(pa0), "+v"(ps)); SBAR();
;   { const bf16x8 k0 = KFRAG(1, 0), k1 = KFRAG(1, 1); n0 = __builtin_amdgcn_mfma_f32_32x32x16_bf16(k0, qr[1], n0, 0, 0, 0); n1 = __builtin_amdgcn_mfma_f32_32x32x16_bf16(k1, qr[1], n1, 0, 0, 0); }
; #pragma unroll
;   for (int r = 8; r < 16; ++r) ps += q0[r];
;   PK4(q0, 8, pa1); asm volatile("" : "+v"(pa1), "+v"(ps)); SBAR();
;   { const bf16x8 k0 = KFRAG(2, 0), k1 = KFRAG(2, 1); n0 = __builtin_amdgcn_mfma_f32_32x32x16_bf16(k0, qr[2], n0, 0, 0, 0); n1 = __builtin_amdgcn_mfma_f32_32x32x16_bf16(k1, qr[2], n1, 0, 0, 0); }
; #pragma unroll
;   for (int r = 0; r < 8; ++r) ps += q1[r];
;   PK4(q1, 0, pa2); asm volatile("" : "+v"(pa2), "+v"(ps)); SBAR();
;   { const bf16x8 k0 = KFRAG(3, 0), k1 = KFRAG(3, 1); n0 = __builtin_amdgcn_mfma_f32_32x32x16_bf16(k0, qr[3], n0, 0, 0, 0); n1 = __builtin_amdgcn_mfma_f32_32x32x16_bf16(k1, qr[3], n1, 0, 0, 0); }
; #pragma unroll
;   for (int r = 8; r < 16; ++r) ps += q1[r];
;   PK4(q1, 8, pa3);
;   { auto rr = __builtin_amdgcn_permlane32_swap(__float_as_uint(ps), __float_as_uint(ps), false, false); ps = __uint_as_float(rr[0]) + __uint_as_float(rr[1]); }
;   l_reg += ps; SBAR();
; }
; template <int D0> __device__ __forceinline__ void pv_one(f32x16& od, int vb, bf16x8 pa0, bf16x8 pa1, bf16x8 pa2, bf16x8 pa3) {
;   const s16x4 l0 = tr_read<v_rd_off(D0, 0, 0)>(vb), h0 = tr_read<v_rd_off(D0, 0, 1)>(vb), l1 = tr_read<v_rd_off(D0, 1, 0)>(vb), h1 = tr_read<v_rd_off(D0, 1, 1)>(vb);
;   const s16x4 l2 = tr_read<v_rd_off(D0, 2, 0)>(vb), h2 = tr_read<v_rd_off(D0, 2, 1)>(vb), l3 = tr_read<v_rd_off(D0, 3, 0)>(vb), h3 = tr_read<v_rd_off(D0, 3, 1)>(vb);
;   asm volatile("s_waitcnt lgkmcnt(0)" ::: "memory"); SBAR();
;     ...
;   od = __builtin_amdgcn_mfma_f32_32x32x16_bf16(pa0, PK(l0, h0), od, 0, 0, 0);
.LBB0_326:
	ds_read_b128 v[248:251], v241 offset:49152
	ds_read_b128 v[214:217], v241 offset:57344
	v_add_f32_e32 v179, 0, v80
	v_add_f32_e32 v179, v81, v179
	v_add_f32_e32 v179, v82, v179
	s_waitcnt lgkmcnt(1)
	v_mfma_f32_32x32x16_bf16 v[112:127], v[248:251], v[132:135], v[112:127]
	v_add_f32_e32 v179, v83, v179
	v_add_f32_e32 v179, v84, v179
	v_add_f32_e32 v179, v85, v179
	v_add_f32_e32 v179, v86, v179
	v_cvt_pk_bf16_f32 v80, v80, v81
	v_cvt_pk_bf16_f32 v81, v82, v83
	v_cvt_pk_bf16_f32 v82, v84, v85
	s_waitcnt lgkmcnt(0)
	v_mfma_f32_32x32x16_bf16 v[96:111], v[214:217], v[132:135], v[96:111]
	v_cvt_pk_bf16_f32 v83, v86, v87
	v_add_f32_e32 v179, v87, v179
	v_permlane32_swap_b32_e32 v80, v82
	v_permlane32_swap_b32_e32 v81, v83
	ds_read_b128 v[84:87], v242 offset:49152
	ds_read_b128 v[214:217], v242 offset:57344
	s_waitcnt lgkmcnt(1)
	v_mfma_f32_32x32x16_bf16 v[112:127], v[84:87], v[128:131], v[112:127]
	v_add_f32_e32 v84, v88, v179
	v_add_f32_e32 v84, v89, v84
	v_add_f32_e32 v84, v90, v84
	v_add_f32_e32 v84, v91, v84
	v_add_f32_e32 v84, v92, v84
	v_add_f32_e32 v84, v93, v84
	v_add_f32_e32 v84, v94, v84
	s_waitcnt lgkmcnt(0)
	v_mfma_f32_32x32x16_bf16 v[96:111], v[214:217], v[128:131], v[96:111]
	v_add_f32_e32 v179, v95, v84
	v_cvt_pk_bf16_f32 v84, v88, v89
	v_cvt_pk_bf16_f32 v85, v90, v91
	v_cvt_pk_bf16_f32 v86, v92, v93
	v_cvt_pk_bf16_f32 v87, v94, v95
	s_nop 0
	v_permlane32_swap_b32_e32 v84, v86
	v_permlane32_swap_b32_e32 v85, v87
	ds_read_b128 v[88:91], v243 offset:49152
	ds_read_b128 v[92:95], v243 offset:57344
	s_waitcnt lgkmcnt(1)
	v_mfma_f32_32x32x16_bf16 v[112:127], v[88:91], v[140:143], v[112:127]
	v_add_f32_e32 v88, v64, v179
	v_add_f32_e32 v88, v65, v88
	v_add_f32_e32 v88, v66, v88
	v_add_f32_e32 v88, v67, v88
	v_add_f32_e32 v88, v68, v88
	v_add_f32_e32 v88, v69, v88
	v_add_f32_e32 v88, v70, v88
	s_waitcnt lgkmcnt(0)
	v_mfma_f32_32x32x16_bf16 v[96:111], v[92:95], v[140:143], v[96:111]
	v_cvt_pk_bf16_f32 v64, v64, v65
	v_cvt_pk_bf16_f32 v65, v66, v67
	v_cvt_pk_bf16_f32 v66, v68, v69
	v_cvt_pk_bf16_f32 v67, v70, v71
	v_add_f32_e32 v92, v71, v88
	v_permlane32_swap_b32_e32 v64, v66
	v_permlane32_swap_b32_e32 v65, v67
	ds_read_b128 v[68:71], v244 offset:49152
	ds_read_b128 v[88:91], v244 offset:57344
	s_waitcnt lgkmcnt(1)
	v_mfma_f32_32x32x16_bf16 v[112:127], v[68:71], v[136:139], v[112:127]
	v_add_f32_e32 v68, v72, v92
	v_add_f32_e32 v68, v73, v68
	v_add_f32_e32 v68, v74, v68
	v_add_f32_e32 v68, v75, v68
	v_add_f32_e32 v68, v76, v68
	v_add_f32_e32 v68, v77, v68
	v_add_f32_e32 v68, v78, v68
	s_waitcnt lgkmcnt(0)
	v_mfma_f32_32x32x16_bf16 v[96:111], v[88:91], v[136:139], v[96:111]
	v_add_f32_e32 v247, v79, v68
	v_mov_b32_e32 v248, v247
	v_cvt_pk_bf16_f32 v68, v72, v73
	v_cvt_pk_bf16_f32 v69, v74, v75
	v_cvt_pk_bf16_f32 v70, v76, v77
	v_cvt_pk_bf16_f32 v71, v78, v79
	s_nop 1
	v_permlane32_swap_b32_e32 v247, v248
	v_permlane32_swap_b32_e32 v68, v70
	v_permlane32_swap_b32_e32 v69, v71
	ds_read_b64_tr_b16 v[72:73], v230 offset:0
	ds_read_b64_tr_b16 v[74:75], v230 offset:0x800
	ds_read_b64_tr_b16 v[76:77], v230 offset:0x1000
	ds_read_b64_tr_b16 v[78:79], v230 offset:0x1800
	ds_read_b64_tr_b16 v[88:89], v230 offset:0x2000
	ds_read_b64_tr_b16 v[90:91], v230 offset:0x2800
	ds_read_b64_tr_b16 v[92:93], v230 offset:0x3000
	ds_read_b64_tr_b16 v[94:95], v230 offset:0x3800
	s_waitcnt lgkmcnt(0)
	s_nop 0
	v_mfma_f32_32x32x16_bf16 v[48:63], v[80:83], v[72:75], v[48:63]
	v_exp_f32_e32 v112, v112
	v_exp_f32_e32 v113, v113
	v_exp_f32_e32 v114, v114
	v_exp_f32_e32 v115, v115
	v_exp_f32_e32 v116, v116
	v_exp_f32_e32 v117, v117
	v_exp_f32_e32 v118, v118
	v_mfma_f32_32x32x16_bf16 v[48:63], v[84:87], v[76:79], v[48:63]
	v_exp_f32_e32 v119, v119
	v_mfma_f32_32x32x16_bf16 v[48:63], v[64:67], v[88:91], v[48:63]
	v_mfma_f32_32x32x16_bf16 v[48:63], v[68:71], v[92:95], v[48:63]
	ds_read_b64_tr_b16 v[72:73], v230 offset:0x200
	ds_read_b64_tr_b16 v[74:75], v230 offset:0xa00
	ds_read_b64_tr_b16 v[76:77], v230 offset:0x1200
	ds_read_b64_tr_b16 v[78:79], v230 offset:0x1a00
	ds_read_b64_tr_b16 v[88:89], v230 offset:0x2200
	ds_read_b64_tr_b16 v[90:91], v230 offset:0x2a00
	ds_read_b64_tr_b16 v[92:93], v230 offset:0x3200
	ds_read_b64_tr_b16 v[94:95], v230 offset:0x3a00
	s_waitcnt lgkmcnt(0)
	s_nop 0
	v_mfma_f32_32x32x16_bf16 v[32:47], v[80:83], v[72:75], v[32:47]
	v_exp_f32_e32 v120, v120
	v_exp_f32_e32 v121, v121
	v_exp_f32_e32 v122, v122
	v_exp_f32_e32 v123, v123
	v_exp_f32_e32 v124, v124
	v_exp_f32_e32 v125, v125
	v_exp_f32_e32 v126, v126
	v_mfma_f32_32x32x16_bf16 v[32:47], v[84:87], v[76:79], v[32:47]
	v_exp_f32_e32 v127, v127
	v_mfma_f32_32x32x16_bf16 v[32:47], v[64:67], v[88:91], v[32:47]
	v_mfma_f32_32x32x16_bf16 v[32:47], v[68:71], v[92:95], v[32:47]
	ds_read_b64_tr_b16 v[72:73], v230 offset:0x400
	ds_read_b64_tr_b16 v[74:75], v230 offset:0xc00
	ds_read_b64_tr_b16 v[76:77], v230 offset:0x1400
	ds_read_b64_tr_b16 v[78:79], v230 offset:0x1c00
	ds_read_b64_tr_b16 v[88:89], v230 offset:0x2400
	ds_read_b64_tr_b16 v[90:91], v230 offset:0x2c00
	ds_read_b64_tr_b16 v[92:93], v230 offset:0x3400
	ds_read_b64_tr_b16 v[94:95], v230 offset:0x3c00
	s_waitcnt lgkmcnt(0)
	s_nop 0
	v_mfma_f32_32x32x16_bf16 v[16:31], v[80:83], v[72:75], v[16:31]
	v_exp_f32_e32 v96, v96
	v_exp_f32_e32 v97, v97
	v_exp_f32_e32 v98, v98
	v_exp_f32_e32 v99, v99
	v_exp_f32_e32 v100, v100
	v_exp_f32_e32 v101, v101
	v_exp_f32_e32 v102, v102
	v_mfma_f32_32x32x16_bf16 v[16:31], v[84:87], v[76:79], v[16:31]
	v_exp_f32_e32 v103, v103
	v_mfma_f32_32x32x16_bf16 v[16:31], v[64:67], v[88:91], v[16:31]
	v_mfma_f32_32x32x16_bf16 v[16:31], v[68:71], v[92:95], v[16:31]
	ds_read_b64_tr_b16 v[72:73], v230 offset:0x600
	ds_read_b64_tr_b16 v[74:75], v230 offset:0xe00
	ds_read_b64_tr_b16 v[76:77], v230 offset:0x1600
	ds_read_b64_tr_b16 v[78:79], v230 offset:0x1e00
	ds_read_b64_tr_b16 v[88:89], v230 offset:0x2600
	ds_read_b64_tr_b16 v[90:91], v230 offset:0x2e00
	ds_read_b64_tr_b16 v[92:93], v230 offset:0x3600
	ds_read_b64_tr_b16 v[94:95], v230 offset:0x3e00
	s_waitcnt lgkmcnt(0)
	s_nop 0
	v_mfma_f32_32x32x16_bf16 v[0:15], v[80:83], v[72:75], v[0:15]
	v_exp_f32_e32 v104, v104
	v_exp_f32_e32 v105, v105
	v_exp_f32_e32 v106, v106
	v_exp_f32_e32 v107, v107
	v_exp_f32_e32 v108, v108
	v_exp_f32_e32 v109, v109
	v_exp_f32_e32 v110, v110
	v_mfma_f32_32x32x16_bf16 v[0:15], v[84:87], v[76:79], v[0:15]
	v_exp_f32_e32 v111, v111
	v_mfma_f32_32x32x16_bf16 v[0:15], v[64:67], v[88:91], v[0:15]
	v_mfma_f32_32x32x16_bf16 v[0:15], v[68:71], v[92:95], v[0:15]
	s_add_i32 s76, s33, 2
	s_barrier
	s_waitcnt vmcnt(4)
	s_cmp_gt_i32 s76, s3
	s_cbranch_scc0 .Lattn_wA
	s_waitcnt vmcnt(0)
; #define SBAR() __builtin_amdgcn_sched_barrier(0)
; #define SLOADA(k0) do { vsA0 = *(const bf16x8*)(&Vh[(size_t)((k0) + sr) * LDP + sc]); vsA1 = *(const bf16x8*)(&Vh[(size_t)((k0) + 32 + sr) * LDP + sc]); \
;     ksA0 = *(const bf16x8*)(&Kh[(size_t)((k0) + sr) * LDP + sc]); ksA1 = *(const bf16x8*)(&Kh[(size_t)((k0) + 32 + sr) * LDP + sc]); } while (0)
; #define SWRITEA(b) do { *(bf16x8*)(V_lds + (b) * SHM_V + vst0) = vsA0; *(bf16x8*)(V_lds + (b) * SHM_V + vst1) = vsA1; const int kc = sc * 2; \
;     *(bf16x8*)(K_lds + (b) * SHM_K + KSWZ(sr, kc)) = ksA0; *(bf16x8*)(K_lds + (b) * SHM_K + KSWZ(32 + sr, kc)) = ksA1; } while (0)
; #define SWAIT() asm volatile("s_waitcnt vmcnt(4)" ::: "memory")
; __device__ __forceinline__ void attn_unit(const bf16* __restrict__ P, bf16* __restrict__ MIXIN, const float* __restrict__ gn, int seq0, int h, int q0, int nt, float kmax0, float kmax1, float slope, float lam, char* lds) {
;     ...
;     __syncthreads(); SWAIT(); SWRITEA(0); __syncthreads();
;     if (j + 3 < t1) SLOADA((j + 3) * 64); SBAR();
.Lattn_wA:
	s_cmp_ge_i32 s76, s3
	s_cselect_b64 s[0:1], -1, 0
	s_and_b64 vcc, exec, s[0:1]
	ds_write_b128 v239, v[144:147]
	ds_write_b128 v240, v[152:155]
	ds_write_b128 v237, v[148:151] offset:32768
	ds_write_b128 v238, v[156:159] offset:32768
	s_waitcnt lgkmcnt(0)
	s_barrier
	s_cbranch_vccnz .LBB0_328
	v_subrev_u32_e32 v64, 32, v246
	v_mad_i64_i32 v[64:65], vcc, v64, s27, 0
	v_or_b32_e32 v64, v64, v185
	v_mad_i64_i32 v[66:67], vcc, v246, s27, 0
	v_lshl_add_u64 v[64:65], v[64:65], 1, s[24:25]
	v_or_b32_e32 v66, v66, v185
	v_lshl_add_u64 v[66:67], v[66:67], 1, s[24:25]
	global_load_dwordx4 v[144:147], v[64:65], off offset:2048
	global_load_dwordx4 v[148:151], v[64:65], off offset:1024
	global_load_dwordx4 v[152:155], v[66:67], off offset:2048
	global_load_dwordx4 v[156:159], v[66:67], off offset:1024

; __device__ __forceinline__ void qk_fin(f32x16& n0, f32x16& n1, const char* Ks, const bf16x8* qr, int r32, int hi, int cbase,
;                                        const f32x16& q0, const f32x16& q1, float& l_reg, bf16x8& pa0, bf16x8& pa1, bf16x8& pa2, bf16x8& pa3) {
;   float ps = 0.f;
;   { const bf16x8 k0 = KFRAG(0, 0), k1 = KFRAG(0, 1); n0 = __builtin_amdgcn_mfma_f32_32x32x16_bf16(k0, qr[0], n0, 0, 0, 0); n1 = __builtin_amdgcn_mfma_f32_32x32x16_bf16(k1, qr[0], n1, 0, 0, 0); }
; #pragma unroll
;   for (int r = 0; r < 8; ++r) ps += q0[r];
;   PK4(q0, 0, pa0); asm volatile("" : "+v"(pa0), "+v"(ps)); SBAR();
;   { const bf16x8 k0 = KFRAG(1, 0), k1 = KFRAG(1, 1); n0 = __builtin_amdgcn_mfma_f32_32x32x16_bf16(k0, qr[1], n0, 0, 0, 0); n1 = __builtin_amdgcn_mfma_f32_32x32x16_bf16(k1, qr[1], n1, 0, 0, 0); }
; #pragma unroll
;   for (int r = 8; r < 16; ++r) ps += q0[r];
;   PK4(q0, 8, pa1); asm volatile("" : "+v"(pa1), "+v"(ps)); SBAR();
;   { const bf16x8 k0 = KFRAG(2, 0), k1 = KFRAG(2, 1); n0 = __builtin_amdgcn_mfma_f32_32x32x16_bf16(k0, qr[2], n0, 0, 0, 0); n1 = __builtin_amdgcn_mfma_f32_32x32x16_bf16(k1, qr[2], n1, 0, 0, 0); }
; #pragma unroll
;   for (int r = 0; r < 8; ++r) ps += q1[r];
;   PK4(q1, 0, pa2); asm volatile("" : "+v"(pa2), "+v"(ps)); SBAR();
;   { const bf16x8 k0 = KFRAG(3, 0), k1 = KFRAG(3, 1); n0 = __builtin_amdgcn_mfma_f32_32x32x16_bf16(k0, qr[3], n0, 0, 0, 0); n1 = __builtin_amdgcn_mfma_f32_32x32x16_bf16(k1, qr[3], n1, 0, 0, 0); }
; #pragma unroll
;   for (int r = 8; r < 16; ++r) ps += q1[r];
;   PK4(q1, 8, pa3);
;   { auto rr = __builtin_amdgcn_permlane32_swap(__float_as_uint(ps), __float_as_uint(ps), false, false); ps = __uint_as_float(rr[0]) + __uint_as_float(rr[1]); }
;   l_reg += ps; SBAR();
; }
; template <int D0> __device__ __forceinline__ void pv_one(f32x16& od, int vb, bf16x8 pa0, bf16x8 pa1, bf16x8 pa2, bf16x8 pa3) {
;   const s16x4 l0 = tr_read<v_rd_off(D0, 0, 0)>(vb), h0 = tr_read<v_rd_off(D0, 0, 1)>(vb), l1 = tr_read<v_rd_off(D0, 1, 0)>(vb), h1 = tr_read<v_rd_off(D0, 1, 1)>(vb);
;   const s16x4 l2 = tr_read<v_rd_off(D0, 2, 0)>(vb), h2 = tr_read<v_rd_off(D0, 2, 1)>(vb), l3 = tr_read<v_rd_off(D0, 3, 0)>(vb), h3 = tr_read<v_rd_off(D0, 3, 1)>(vb);
;   asm volatile("s_waitcnt lgkmcnt(0)" ::: "memory"); SBAR();
;     ...
;   od = __builtin_amdgcn_mfma_f32_32x32x16_bf16(pa0, PK(l0, h0), od, 0, 0, 0);
.LBB0_331:
	v_add_f32_e32 v179, v247, v248
	v_add_f32_e32 v179, v231, v179
	ds_read_b128 v[214:217], v241 offset:32768
	ds_read_b128 v[248:251], v241 offset:40960
	v_add_f32_e32 v181, 0, v112
	v_add_f32_e32 v181, v113, v181
	v_add_f32_e32 v181, v114, v181
	s_waitcnt lgkmcnt(1)
	v_mfma_f32_32x32x16_bf16 v[80:95], v[214:217], v[132:135], v[80:95]
	v_add_f32_e32 v181, v115, v181
	v_add_f32_e32 v181, v116, v181
	v_add_f32_e32 v181, v117, v181
	v_add_f32_e32 v181, v118, v181
	v_cvt_pk_bf16_f32 v112, v112, v113
	v_cvt_pk_bf16_f32 v113, v114, v115
	v_cvt_pk_bf16_f32 v114, v116, v117
	s_waitcnt lgkmcnt(0)
	v_mfma_f32_32x32x16_bf16 v[64:79], v[248:251], v[132:135], v[64:79]
	v_cvt_pk_bf16_f32 v115, v118, v119
	v_add_f32_e32 v181, v119, v181
	v_permlane32_swap_b32_e32 v112, v114
	v_permlane32_swap_b32_e32 v113, v115
	ds_read_b128 v[116:119], v242 offset:32768
	ds_read_b128 v[214:217], v242 offset:40960
	s_waitcnt lgkmcnt(1)
	v_mfma_f32_32x32x16_bf16 v[80:95], v[116:119], v[128:131], v[80:95]
	v_add_f32_e32 v116, v120, v181
	v_add_f32_e32 v116, v121, v116
	v_add_f32_e32 v116, v122, v116
	v_add_f32_e32 v116, v123, v116
	v_add_f32_e32 v116, v124, v116
	v_add_f32_e32 v116, v125, v116
	v_add_f32_e32 v116, v126, v116
	s_waitcnt lgkmcnt(0)
	v_mfma_f32_32x32x16_bf16 v[64:79], v[214:217], v[128:131], v[64:79]
	v_add_f32_e32 v181, v127, v116
	v_cvt_pk_bf16_f32 v116, v120, v121
	v_cvt_pk_bf16_f32 v117, v122, v123
	v_cvt_pk_bf16_f32 v118, v124, v125
	v_cvt_pk_bf16_f32 v119, v126, v127
	s_nop 0
	v_permlane32_swap_b32_e32 v116, v118
	v_permlane32_swap_b32_e32 v117, v119
	ds_read_b128 v[120:123], v243 offset:32768
	ds_read_b128 v[124:127], v243 offset:40960
	s_waitcnt lgkmcnt(1)
	v_mfma_f32_32x32x16_bf16 v[80:95], v[120:123], v[140:143], v[80:95]
	v_add_f32_e32 v120, v96, v181
	v_add_f32_e32 v120, v97, v120
	v_add_f32_e32 v120, v98, v120
	v_add_f32_e32 v120, v99, v120
	v_add_f32_e32 v120, v100, v120
	v_add_f32_e32 v120, v101, v120
	v_add_f32_e32 v120, v102, v120
	s_waitcnt lgkmcnt(0)
	v_mfma_f32_32x32x16_bf16 v[64:79], v[124:127], v[140:143], v[64:79]
	v_cvt_pk_bf16_f32 v96, v96, v97
	v_cvt_pk_bf16_f32 v97, v98, v99
	v_cvt_pk_bf16_f32 v98, v100, v101
	v_cvt_pk_bf16_f32 v99, v102, v103
	v_add_f32_e32 v124, v103, v120
	v_permlane32_swap_b32_e32 v96, v98
	v_permlane32_swap_b32_e32 v97, v99
	ds_read_b128 v[100:103], v244 offset:32768
	ds_read_b128 v[120:123], v244 offset:40960
	s_waitcnt lgkmcnt(1)
	v_mfma_f32_32x32x16_bf16 v[80:95], v[100:103], v[136:139], v[80:95]
	v_add_f32_e32 v100, v104, v124
	v_add_f32_e32 v100, v105, v100
	v_add_f32_e32 v100, v106, v100
	v_add_f32_e32 v100, v107, v100
	v_add_f32_e32 v100, v108, v100
	v_add_f32_e32 v100, v109, v100
	v_add_f32_e32 v100, v110, v100
	s_waitcnt lgkmcnt(0)
	v_mfma_f32_32x32x16_bf16 v[64:79], v[120:123], v[136:139], v[64:79]
	v_add_f32_e32 v120, v111, v100
	v_cvt_pk_bf16_f32 v100, v104, v105
	v_mov_b32_e32 v104, v120
	s_nop 1
	v_permlane32_swap_b32_e32 v120, v104
	v_add_f32_e32 v104, v120, v104
	v_cvt_pk_bf16_f32 v101, v106, v107
	v_cvt_pk_bf16_f32 v102, v108, v109
	v_cvt_pk_bf16_f32 v103, v110, v111
	v_add_f32_e32 v231, v179, v104
	v_permlane32_swap_b32_e32 v100, v102
	v_permlane32_swap_b32_e32 v101, v103
	ds_read_b64_tr_b16 v[104:105], v245 offset:0
	ds_read_b64_tr_b16 v[106:107], v245 offset:0x800
	ds_read_b64_tr_b16 v[108:109], v245 offset:0x1000
	ds_read_b64_tr_b16 v[110:111], v245 offset:0x1800
	ds_read_b64_tr_b16 v[120:121], v245 offset:0x2000
	ds_read_b64_tr_b16 v[122:123], v245 offset:0x2800
	ds_read_b64_tr_b16 v[124:125], v245 offset:0x3000
	ds_read_b64_tr_b16 v[126:127], v245 offset:0x3800
	s_waitcnt lgkmcnt(0)
	s_nop 0
	v_mfma_f32_32x32x16_bf16 v[48:63], v[112:115], v[104:107], v[48:63]
	v_exp_f32_e32 v80, v80
	v_exp_f32_e32 v81, v81
	v_exp_f32_e32 v82, v82
	v_exp_f32_e32 v83, v83
	v_exp_f32_e32 v84, v84
	v_exp_f32_e32 v85, v85
	v_exp_f32_e32 v86, v86
	v_mfma_f32_32x32x16_bf16 v[48:63], v[116:119], v[108:111], v[48:63]
	v_exp_f32_e32 v87, v87
	v_mfma_f32_32x32x16_bf16 v[48:63], v[96:99], v[120:123], v[48:63]
	v_mfma_f32_32x32x16_bf16 v[48:63], v[100:103], v[124:127], v[48:63]
	ds_read_b64_tr_b16 v[104:105], v245 offset:0x200
	ds_read_b64_tr_b16 v[106:107], v245 offset:0xa00
	ds_read_b64_tr_b16 v[108:109], v245 offset:0x1200
	ds_read_b64_tr_b16 v[110:111], v245 offset:0x1a00
	ds_read_b64_tr_b16 v[120:121], v245 offset:0x2200
	ds_read_b64_tr_b16 v[122:123], v245 offset:0x2a00
	ds_read_b64_tr_b16 v[124:125], v245 offset:0x3200
	ds_read_b64_tr_b16 v[126:127], v245 offset:0x3a00
	s_waitcnt lgkmcnt(0)
	s_nop 0
	v_mfma_f32_32x32x16_bf16 v[32:47], v[112:115], v[104:107], v[32:47]
	v_exp_f32_e32 v88, v88
	v_exp_f32_e32 v89, v89
	v_exp_f32_e32 v90, v90
	v_exp_f32_e32 v91, v91
	v_exp_f32_e32 v92, v92
	v_exp_f32_e32 v93, v93
	v_exp_f32_e32 v94, v94
	v_mfma_f32_32x32x16_bf16 v[32:47], v[116:119], v[108:111], v[32:47]
	v_exp_f32_e32 v95, v95
	v_mfma_f32_32x32x16_bf16 v[32:47], v[96:99], v[120:123], v[32:47]
	v_mfma_f32_32x32x16_bf16 v[32:47], v[100:103], v[124:127], v[32:47]
	ds_read_b64_tr_b16 v[104:105], v245 offset:0x400
	ds_read_b64_tr_b16 v[106:107], v245 offset:0xc00
	ds_read_b64_tr_b16 v[108:109], v245 offset:0x1400
	ds_read_b64_tr_b16 v[110:111], v245 offset:0x1c00
	ds_read_b64_tr_b16 v[120:121], v245 offset:0x2400
	ds_read_b64_tr_b16 v[122:123], v245 offset:0x2c00
	ds_read_b64_tr_b16 v[124:125], v245 offset:0x3400
	ds_read_b64_tr_b16 v[126:127], v245 offset:0x3c00
	s_waitcnt lgkmcnt(0)
	s_nop 0
	v_mfma_f32_32x32x16_bf16 v[16:31], v[112:115], v[104:107], v[16:31]
	v_exp_f32_e32 v64, v64
	v_exp_f32_e32 v65, v65
	v_exp_f32_e32 v66, v66
	v_exp_f32_e32 v67, v67
	v_exp_f32_e32 v68, v68
	v_exp_f32_e32 v69, v69
	v_exp_f32_e32 v70, v70
	v_mfma_f32_32x32x16_bf16 v[16:31], v[116:119], v[108:111], v[16:31]
	v_exp_f32_e32 v71, v71
	v_mfma_f32_32x32x16_bf16 v[16:31], v[96:99], v[120:123], v[16:31]
	v_mfma_f32_32x32x16_bf16 v[16:31], v[100:103], v[124:127], v[16:31]
	ds_read_b64_tr_b16 v[104:105], v245 offset:0x600
	ds_read_b64_tr_b16 v[106:107], v245 offset:0xe00
	ds_read_b64_tr_b16 v[108:109], v245 offset:0x1600
	ds_read_b64_tr_b16 v[110:111], v245 offset:0x1e00
	ds_read_b64_tr_b16 v[120:121], v245 offset:0x2600
	ds_read_b64_tr_b16 v[122:123], v245 offset:0x2e00
	ds_read_b64_tr_b16 v[124:125], v245 offset:0x3600
	ds_read_b64_tr_b16 v[126:127], v245 offset:0x3e00
	s_waitcnt lgkmcnt(0)
	s_nop 0
	v_mfma_f32_32x32x16_bf16 v[0:15], v[112:115], v[104:107], v[0:15]
	v_exp_f32_e32 v72, v72
	v_exp_f32_e32 v73, v73
	v_exp_f32_e32 v74, v74
	v_exp_f32_e32 v75, v75
	v_exp_f32_e32 v76, v76
	v_exp_f32_e32 v77, v77
	v_exp_f32_e32 v78, v78
	v_mfma_f32_32x32x16_bf16 v[0:15], v[116:119], v[108:111], v[0:15]
	v_exp_f32_e32 v79, v79
	v_mfma_f32_32x32x16_bf16 v[0:15], v[96:99], v[120:123], v[0:15]
	v_mfma_f32_32x32x16_bf16 v[0:15], v[100:103], v[124:127], v[0:15]
	s_barrier
	s_waitcnt vmcnt(4)
	v_add_u32_e32 v246, 0x80, v246
	s_and_b64 vcc, exec, s[0:1]
	s_cbranch_vccz .Lattn_wB
	s_waitcnt vmcnt(0)
; #define SWRITEB(b) do { *(bf16x8*)(V_lds + (b) * SHM_V + vst0) = vsB0; *(bf16x8*)(V_lds + (b) * SHM_V + vst1) = vsB1; const int kc = sc * 2; \
;     *(bf16x8*)(K_lds + (b) * SHM_K + KSWZ(sr, kc)) = ksB0; *(bf16x8*)(K_lds + (b) * SHM_K + KSWZ(32 + sr, kc)) = ksB1; } while (0)
; #define SWAIT() asm volatile("s_waitcnt vmcnt(4)" ::: "memory")
; __device__ __forceinline__ void attn_unit(const bf16* __restrict__ P, bf16* __restrict__ MIXIN, const float* __restrict__ gn, int seq0, int h, int q0, int nt, float kmax0, float kmax1, float slope, float lam, char* lds) {
;     ...
;     __syncthreads(); SWAIT(); SWRITEB(1); __syncthreads();
;   }
.Lattn_wB:
	ds_write_b128 v239, v[160:163] offset:16384
	ds_write_b128 v240, v[168:171] offset:16384
	ds_write_b128 v237, v[164:167] offset:49152
	ds_write_b128 v238, v[172:175] offset:49152
	s_waitcnt lgkmcnt(0)
	s_barrier
	s_cbranch_vccnz .LBB0_336
	s_mov_b32 s33, s76
	s_add_i32 s0, s33, 1
	s_cmp_ge_i32 s0, s3
	s_cbranch_scc0 .LBB0_322
	s_branch .LBB0_323
